# code placement: 4-byte phase of the hand-written diff loop flipped as well (on top of the retention loop flip)
# baseline (speedup 1.0000x reference)
; #define ATT_WAITBAR_ONE() do { if (DIFF) asm volatile("s_waitcnt vmcnt(4) lgkmcnt(0)\n\ts_barrier" ::: "memory"); else asm volatile("s_waitcnt vmcnt(3) lgkmcnt(0)\n\ts_barrier" ::: "memory"); } while (0)
; template <bool DIFF>
; __device__ __forceinline__ void attn_item(LAS unsigned char* lds, const bf16_t* Z, bf16_t* MIX, int b, int h, int t, float lam, float shift, const float* gain, int tid, int wid, int lane) {
;     ...
;     ATT_DMA(0, 0); ATT_DMA(1, 1);
;     ATT_WAITBAR_ONE();
;     const unsigned kfo = (unsigned)(q16 * 128), ksw = (unsigned)(q16 & 7);
;     const unsigned vrr = (unsigned)(4 * quad + (q16 >> 2)), vx32 = (vrr & 7u) * 32u, vb0 = 16384u + vrr * 256u + 8u * (unsigned)(q16 & 3);
;     const float iq = (float)(128 * t + 16 * wid + q16);
;     int bcur = 0;
;     for (int kt = 0; kt < nkt; ++kt) {
.Ldx_b0:
	s_barrier
	s_mov_b32 s15, 1
	s_nop 0

; #define ATT_KREAD(dst, c) do { _Pragma("unroll") for (int kb = 0; kb < 4; ++kb) _Pragma("unroll") for (int ds = 0; ds < 2; ++ds) \
;                 dst[kb * 2 + ds] = *(const LAS bf16x8*)(bp + (c) * 8192 + kb * 2048 + kfo + (((unsigned)(4 * ds + quad) ^ ksw) * 16)); } while (0)
; #define ATT_SMMA(sv, kf, c) do { _Pragma("unroll") for (int kb = 0; kb < 4; ++kb) { sv[kb] = (f32x4){sinit, sinit, sinit, sinit}; _Pragma("unroll") for (int ds = 0; ds < 2; ++ds) \
;                 sv[kb] = __builtin_amdgcn_mfma_f32_16x16x32_bf16(kf[kb * 2 + ds], qf[c][ds], sv[kb], 0, 0, 0); } } while (0)
; #define ATT_PV(c, lo_, hi_, eb0) do { _Pragma("unroll") for (int e = 0; e < 4; ++e) _Pragma("unroll") for (int ks = 0; ks < 2; ++ks) \
;                 O[c][(eb0) + e] = __builtin_amdgcn_mfma_f32_16x16x32_bf16(__builtin_shufflevector(lo_[e * 2 + ks], hi_[e * 2 + ks], 0, 1, 2, 3, 4, 5, 6, 7), P[c][ks], O[c][(eb0) + e], 0, 0, 0); } while (0)
; #define ATT_PVW(c, lo_, hi_, eb0) do { ATT_W4(12, lo_, hi_, 0); ATT_PV1(c, lo_, hi_, eb0, 0); ATT_W4(8, lo_, hi_, 1); ATT_PV1(c, lo_, hi_, eb0, 1); \
;                 ATT_W4(4, lo_, hi_, 2); ATT_PV1(c, lo_, hi_, eb0, 2); ATT_W4(0, lo_, hi_, 3); ATT_PV1(c, lo_, hi_, eb0, 3); } while (0)
; #define ATT_SB __builtin_amdgcn_sched_barrier(0)
; template <bool DIFF>
; __device__ __forceinline__ void attn_item(LAS unsigned char* lds, const bf16_t* Z, bf16_t* MIX, int b, int h, int t, float lam, float shift, const float* gain, int tid, int wid, int lane) {
;     ...
;             ATT_KREAD(kfA, 0); ATT_SB;
;             if (DIFF) { ATT_KREAD(kfB, NC - 1); ATT_SMMA(s0, kfA, 0); ATT_SB;
;                         ATT_VISSUE(vAl, vAh, 0); ATT_SMMA(s1, kfB, NC - 1); ATT_SOFT(s0, 0); ATT_SB;
;                         ATT_SOFT(s1, NC - 1); ATT_PVW(0, vAl, vAh, 0); ATT_SB;
;                         ATT_VISSUE(vBl, vBh, 4); ATT_PV(NC - 1, vAl, vAh, 0); ATT_SB;
;                         ATT_PVW(0, vBl, vBh, 4); ATT_PV(NC - 1, vBl, vBh, 4); ATT_SB; }
.Ldx_bar:
	s_barrier
	s_branch .Ldx_loop
	s_nop 0
.Ldx_exit:
	s_add_i32 s2, s70, 1
	s_cmp_le_u32 s2, s83
	s_cbranch_scc0 .Ldx_done
	s_and_b32 s1, s2, 3
	s_lshl_b32 s1, s1, 15
	s_waitcnt lgkmcnt(0)
	v_add_u32_e32 v118, s1, v143
	v_add_u32_e32 v120, v118, v138
	v_add_u32_e32 v121, v118, v137
	v_add_u32_e32 v122, v118, v136
	v_add_u32_e32 v123, v118, v129
	v_mfma_f32_16x16x32_bf16 v[64:67], v[148:151], v[220:223], v[64:67]
	v_add_f32_e32 v131, v131, v188
	v_add_f32_e32 v131, v131, v189
	v_mfma_f32_16x16x32_bf16 v[60:63], v[156:159], v[220:223], v[60:63]
	v_add_f32_e32 v131, v131, v190
	v_add_f32_e32 v131, v131, v191
	v_mfma_f32_16x16x32_bf16 v[56:59], v[148:151], v[228:231], v[56:59]
	v_add_f32_e32 v131, v131, v192
	v_add_f32_e32 v131, v131, v193
	v_mfma_f32_16x16x32_bf16 v[52:55], v[156:159], v[228:231], v[52:55]
	v_add_f32_e32 v131, v131, v194
	v_add_f32_e32 v131, v131, v195
	v_mfma_f32_16x16x32_bf16 v[64:67], v[152:155], v[224:227], v[64:67]
	v_add_f32_e32 v131, v131, v196
	v_add_f32_e32 v131, v131, v197
	v_mfma_f32_16x16x32_bf16 v[60:63], v[160:163], v[224:227], v[60:63]
	v_add_f32_e32 v131, v131, v198
	v_add_f32_e32 v131, v131, v199
	v_mfma_f32_16x16x32_bf16 v[56:59], v[152:155], v[232:235], v[56:59]
	v_add_f32_e32 v131, v131, v200
	v_add_f32_e32 v131, v131, v201
	v_mfma_f32_16x16x32_bf16 v[52:55], v[160:163], v[232:235], v[52:55]
	v_add_f32_e32 v131, v131, v202
	v_add_f32_e32 v131, v131, v203
	ds_read_b64_tr_b16 v[148:149], v120
	ds_read_b64_tr_b16 v[150:151], v120 offset:4096
	ds_read_b64_tr_b16 v[152:153], v120 offset:8192
	ds_read_b64_tr_b16 v[154:155], v120 offset:12288
	ds_read_b64_tr_b16 v[156:157], v121
	ds_read_b64_tr_b16 v[158:159], v121 offset:4096
	ds_read_b64_tr_b16 v[160:161], v121 offset:8192
	ds_read_b64_tr_b16 v[162:163], v121 offset:12288
	v_mfma_f32_16x16x32_bf16 v[48:51], v[164:167], v[220:223], v[48:51]
	v_add_f32_e32 v130, v130, v204
	v_add_f32_e32 v130, v130, v205
	v_mfma_f32_16x16x32_bf16 v[40:43], v[172:175], v[220:223], v[40:43]
	v_add_f32_e32 v130, v130, v206
	v_add_f32_e32 v130, v130, v207
	v_mfma_f32_16x16x32_bf16 v[44:47], v[164:167], v[228:231], v[44:47]
	v_add_f32_e32 v130, v130, v208
	v_add_f32_e32 v130, v130, v209
	v_mfma_f32_16x16x32_bf16 v[36:39], v[172:175], v[228:231], v[36:39]
	v_add_f32_e32 v130, v130, v210
	v_add_f32_e32 v130, v130, v211
	v_mfma_f32_16x16x32_bf16 v[48:51], v[168:171], v[224:227], v[48:51]
	v_add_f32_e32 v130, v130, v212
	v_add_f32_e32 v130, v130, v213
	v_mfma_f32_16x16x32_bf16 v[40:43], v[176:179], v[224:227], v[40:43]
	v_add_f32_e32 v130, v130, v214
	v_add_f32_e32 v130, v130, v215
	v_mfma_f32_16x16x32_bf16 v[44:47], v[168:171], v[232:235], v[44:47]
	v_add_f32_e32 v130, v130, v216
	v_add_f32_e32 v130, v130, v217
	v_mfma_f32_16x16x32_bf16 v[36:39], v[176:179], v[232:235], v[36:39]
	v_add_f32_e32 v130, v130, v218
	v_add_f32_e32 v130, v130, v219
	ds_read_b64_tr_b16 v[164:165], v122
	ds_read_b64_tr_b16 v[166:167], v122 offset:4096
	ds_read_b64_tr_b16 v[168:169], v122 offset:8192
	ds_read_b64_tr_b16 v[170:171], v122 offset:12288
	ds_read_b64_tr_b16 v[172:173], v123
	ds_read_b64_tr_b16 v[174:175], v123 offset:4096
	ds_read_b64_tr_b16 v[176:177], v123 offset:8192
	ds_read_b64_tr_b16 v[178:179], v123 offset:12288
	s_waitcnt lgkmcnt(8)
	v_mfma_f32_16x16x32_bf16 v[32:35], v[148:151], v[220:223], v[32:35]
	v_mfma_f32_16x16x32_bf16 v[24:27], v[156:159], v[220:223], v[24:27]
	v_mfma_f32_16x16x32_bf16 v[28:31], v[148:151], v[228:231], v[28:31]
	v_mfma_f32_16x16x32_bf16 v[20:23], v[156:159], v[228:231], v[20:23]
	v_mfma_f32_16x16x32_bf16 v[32:35], v[152:155], v[224:227], v[32:35]
	v_mfma_f32_16x16x32_bf16 v[24:27], v[160:163], v[224:227], v[24:27]
	v_mfma_f32_16x16x32_bf16 v[28:31], v[152:155], v[232:235], v[28:31]
	v_mfma_f32_16x16x32_bf16 v[20:23], v[160:163], v[232:235], v[20:23]
	s_waitcnt lgkmcnt(0)
	v_mfma_f32_16x16x32_bf16 v[16:19], v[164:167], v[220:223], v[16:19]
	v_mfma_f32_16x16x32_bf16 v[8:11], v[172:175], v[220:223], v[8:11]
	v_mfma_f32_16x16x32_bf16 v[12:15], v[164:167], v[228:231], v[12:15]
	v_mfma_f32_16x16x32_bf16 v[4:7], v[172:175], v[228:231], v[4:7]
	v_mfma_f32_16x16x32_bf16 v[16:19], v[168:171], v[224:227], v[16:19]
	v_mfma_f32_16x16x32_bf16 v[8:11], v[176:179], v[224:227], v[8:11]
	v_mfma_f32_16x16x32_bf16 v[12:15], v[168:171], v[232:235], v[12:15]
	v_mfma_f32_16x16x32_bf16 v[4:7], v[176:179], v[232:235], v[4:7]
